# ssd_sample setup: z loop's two loads in flight together; A_log load issued with the dt loads
# baseline (speedup 1.0000x reference)
.LBB0_301:
	s_or_b64 exec, exec, s[10:11]
	s_movk_i32 s10, 0x400
	v_cmp_gt_i32_e32 vcc, s10, v75
	s_and_saveexec_b64 s[10:11], vcc
	s_cbranch_execz .LBB0_304
	s_lshl_b32 s12, s4, 10
	s_add_u32 s12, s60, s12
	s_addc_u32 s13, s61, 0
	v_lshlrev_b32_e32 v2, 1, v75
	s_mov_b64 s[14:15], 0
	v_mov_b32_e32 v3, v75
	s_mov_b32 s97, 0
.LBB0_303:
	v_ashrrev_i32_e32 v4, 8, v3
	v_ashrrev_i32_e32 v5, 31, v4
	v_mov_b64_e32 v[6:7], s[12:13]
	v_lshl_add_u64 v[8:9], s[6:7], 0, v[4:5]
	v_and_b32_e32 v10, 0x1fe, v2
	v_mad_u64_u32 v[6:7], s[16:17], v8, s28, v[6:7]
	v_lshlrev_b32_e32 v50, 1, v10
	v_mad_i32_i24 v7, v9, s28, v7
	v_lshl_add_u64 v[6:7], v[6:7], 0, v[50:51]
	s_cmp_eq_u32 s97, 0
	s_cbranch_scc0 .Lsmpz_second
	global_load_dword v5, v[6:7], off
	v_add_co_u32_e32 v6, vcc, 0x4800, v6
	v_addc_co_u32_e32 v7, vcc, 0, v7, vcc
	global_load_dword v255, v[6:7], off
	s_mov_b32 s97, 1
	s_branch .Lsmpz_join
.Lsmpz_second:
	v_mov_b32_e32 v5, v255
.Lsmpz_join:
	v_add_u32_e32 v6, 0x200, v3
	v_cmp_lt_i32_e32 vcc, s29, v3
	v_lshlrev_b32_e32 v4, 11, v4
	v_lshlrev_b32_e32 v7, 2, v10
	v_add_u32_e32 v2, 0x400, v2
	s_or_b64 s[14:15], vcc, s[14:15]
	v_mov_b32_e32 v3, v6
	v_add3_u32 v6, 0, v4, v7
	s_waitcnt vmcnt(0)
	v_lshlrev_b32_e32 v4, 16, v5
	v_and_b32_e32 v5, 0xffff0000, v5
	ds_write_b64 v6, v[4:5] offset:20864
	s_andn2_b64 exec, exec, s[14:15]
	s_cbranch_execnz .LBB0_303
.LBB0_304:
	s_or_b64 exec, exec, s[10:11]
	v_cmp_lt_i32_e32 vcc, 31, v75
	s_and_saveexec_b64 s[10:11], vcc
	s_xor_b64 s[10:11], exec, s[10:11]
	v_lshrrev_b32_e32 v50, 3, v75
	v_mov_b32_e32 v18, v50
	v_mov_b64_e32 v[2:3], v[50:51]
	s_or_saveexec_b64 s[10:11], s[10:11]
	s_lshl_b32 s14, s4, 3
	v_and_b32_e32 v21, 7, v75
	s_xor_b64 exec, exec, s[10:11]
	s_cbranch_execz .LBB0_310
	v_ashrrev_i32_e32 v18, 3, v75
	v_ashrrev_i32_e32 v19, 31, v18
	v_lshl_add_u64 v[2:3], s[6:7], 0, v[18:19]
	v_readlane_b32 s12, v242, 57
	v_or_b32_e32 v4, s14, v21
	v_lshlrev_b64 v[2:3], 6, v[2:3]
	v_readlane_b32 s13, v242, 58
	v_lshlrev_b32_e32 v50, 2, v4
	v_readlane_b32 s36, v242, 2
	v_lshl_add_u64 v[2:3], s[12:13], 0, v[2:3]
	v_lshl_add_u64 v[2:3], v[2:3], 0, v[50:51]
	v_readlane_b32 s44, v242, 10
	v_readlane_b32 s45, v242, 11
	v_readlane_b32 s46, v242, 12
	v_readlane_b32 s47, v242, 13
	s_nop 4
	global_load_dword v4, v50, s[44:45]
	s_nop 0
	global_load_dword v2, v[2:3], off
	global_load_dword v254, v50, s[46:47]
	s_mov_b32 s12, 0x41a00000
	v_readlane_b32 s37, v242, 3
	v_readlane_b32 s38, v242, 4
	v_readlane_b32 s39, v242, 5
	v_readlane_b32 s40, v242, 6
	v_readlane_b32 s41, v242, 7
	v_readlane_b32 s42, v242, 8
	v_readlane_b32 s43, v242, 9
	v_readlane_b32 s46, v242, 12
	v_readlane_b32 s47, v242, 13
	v_readlane_b32 s48, v242, 14
	v_readlane_b32 s49, v242, 15
	v_readlane_b32 s50, v242, 16
	v_readlane_b32 s51, v242, 17
	s_waitcnt vmcnt(0)
	v_add_f32_e32 v2, v2, v4
	v_cmp_nlt_f32_e32 vcc, s12, v2
	s_and_saveexec_b64 s[12:13], vcc
	s_cbranch_execz .LBB0_309
	v_mul_f32_e32 v2, 0x3fb8aa3b, v2
	v_exp_f32_e32 v16, v2
	s_mov_b32 s15, 0x3f2aaaab
	v_add_f32_e32 v4, 1.0, v16
	v_frexp_mant_f32_e32 v6, v4
	v_cvt_f64_f32_e32 v[2:3], v4
	v_frexp_exp_i32_f64_e32 v2, v[2:3]
	v_cmp_gt_f32_e32 vcc, s15, v6
	v_add_f32_e32 v5, -1.0, v4
	v_sub_f32_e32 v7, v5, v4
	v_subbrev_co_u32_e32 v10, vcc, 0, v2, vcc
	v_sub_u32_e32 v2, 0, v10
	v_sub_f32_e32 v5, v16, v5
	v_add_f32_e32 v7, 1.0, v7
	v_ldexp_f32 v3, v4, v2
	v_add_f32_e32 v5, v5, v7
	v_add_f32_e32 v4, -1.0, v3
	v_add_f32_e32 v6, 1.0, v3
	v_ldexp_f32 v2, v5, v2
	v_add_f32_e32 v5, 1.0, v4
	v_add_f32_e32 v7, -1.0, v6
	v_sub_f32_e32 v5, v3, v5
	v_sub_f32_e32 v3, v3, v7
	v_add_f32_e32 v5, v2, v5
	v_add_f32_e32 v2, v2, v3
	v_add_f32_e32 v11, v6, v2
	v_rcp_f32_e32 v13, v11
	v_sub_f32_e32 v3, v11, v6
	v_sub_f32_e32 v12, v2, v3
	v_add_f32_e32 v3, v4, v5
	v_mul_f32_e32 v15, v3, v13
	v_sub_f32_e32 v2, v3, v4
	v_mul_f32_e32 v4, v11, v15
	v_fma_f32 v6, v15, v11, -v4
	v_fmac_f32_e32 v6, v15, v12
	v_sub_f32_e32 v14, v5, v2
	v_add_f32_e32 v2, v4, v6
	v_sub_f32_e32 v5, v3, v2
	v_pk_add_f32 v[8:9], v[2:3], v[4:5] neg_lo:[0,1] neg_hi:[0,1]
	v_mov_b32_e32 v7, v2
	v_pk_add_f32 v[2:3], v[8:9], v[6:7] neg_lo:[0,1] neg_hi:[0,1]
	s_mov_b32 s15, 0x3f317218
	v_add_f32_e32 v3, v14, v3
	v_add_f32_e32 v2, v2, v3
	v_add_f32_e32 v3, v5, v2
	v_mul_f32_e32 v14, v13, v3
	v_mul_f32_e32 v4, v11, v14
	v_fma_f32 v6, v14, v11, -v4
	v_fmac_f32_e32 v6, v14, v12
	v_sub_f32_e32 v5, v5, v3
	v_add_f32_e32 v11, v2, v5
	v_add_f32_e32 v2, v4, v6
	v_sub_f32_e32 v5, v3, v2
	v_pk_add_f32 v[8:9], v[2:3], v[4:5] neg_lo:[0,1] neg_hi:[0,1]
	v_mov_b32_e32 v7, v2
	v_pk_add_f32 v[2:3], v[8:9], v[6:7] neg_lo:[0,1] neg_hi:[0,1]
	s_nop 0
	v_add_f32_e32 v3, v11, v3
	v_add_f32_e32 v2, v2, v3
	v_add_f32_e32 v3, v15, v14
	v_add_f32_e32 v2, v5, v2
	v_sub_f32_e32 v4, v3, v15
	v_mul_f32_e32 v2, v13, v2
	v_sub_f32_e32 v4, v14, v4
	v_add_f32_e32 v4, v4, v2
	v_add_f32_e32 v6, v3, v4
	v_mul_f32_e32 v7, v6, v6
	v_fmamk_f32 v2, v7, 0x3e9b6dac, v70
	v_fmaak_f32 v53, v7, v2, 0x3f2aaada
	v_cvt_f32_i32_e32 v2, v10
	v_sub_f32_e32 v3, v6, v3
	v_sub_f32_e32 v3, v4, v3
	v_ldexp_f32 v8, v3, 1
	v_mul_f32_e32 v3, v6, v7
	v_ldexp_f32 v5, v6, 1
	v_pk_mul_f32 v[6:7], v[2:3], v[52:53]
	s_nop 0
	v_fma_f32 v4, v2, s15, -v6
	v_fmac_f32_e32 v4, 0xb102e308, v2
	v_pk_add_f32 v[2:3], v[6:7], v[4:5]
	s_mov_b32 s15, 0x7f800000
	v_sub_f32_e32 v5, v3, v5
	v_sub_f32_e32 v5, v7, v5
	v_add_f32_e32 v9, v8, v5
	v_mov_b32_e32 v8, v6
	v_pk_add_f32 v[6:7], v[2:3], v[6:7] neg_lo:[0,1] neg_hi:[0,1]
	v_pk_add_f32 v[10:11], v[2:3], v[8:9]
	v_mov_b32_e32 v5, v2
	v_mov_b32_e32 v7, v11
	v_pk_add_f32 v[12:13], v[4:5], v[6:7] neg_lo:[0,1] neg_hi:[0,1]
	v_pk_add_f32 v[4:5], v[4:5], v[6:7]
	v_mov_b32_e32 v8, v9
	v_pk_add_f32 v[6:7], v[4:5], v[2:3] op_sel:[1,0] op_sel_hi:[0,1] neg_lo:[0,1] neg_hi:[0,1]
	v_pk_add_f32 v[14:15], v[10:11], v[6:7] op_sel_hi:[1,0] neg_lo:[0,1] neg_hi:[0,1]
	v_mov_b32_e32 v10, v11
	v_mov_b32_e32 v11, v5
	v_pk_mov_b32 v[6:7], v[2:3], v[6:7] op_sel:[1,0]
	v_mov_b32_e32 v9, v2
	v_pk_add_f32 v[6:7], v[10:11], v[6:7] neg_lo:[0,1] neg_hi:[0,1]
	v_mov_b32_e32 v14, v12
	v_pk_add_f32 v[2:3], v[8:9], v[6:7] neg_lo:[0,1] neg_hi:[0,1]
	v_mov_b32_e32 v13, v5
	v_pk_add_f32 v[6:7], v[14:15], v[2:3]
	v_cmp_neq_f32_e32 vcc, s15, v16
	v_pk_add_f32 v[8:9], v[6:7], v[6:7] op_sel:[0,1] op_sel_hi:[1,0]
	s_mov_b32 s15, 0x33800000
	v_pk_add_f32 v[4:5], v[4:5], v[8:9] op_sel:[1,0] op_sel_hi:[0,1]
	v_mov_b32_e32 v7, v4
	v_pk_add_f32 v[10:11], v[6:7], v[12:13] neg_lo:[0,1] neg_hi:[0,1]
	v_mov_b32_e32 v3, v8
	v_sub_f32_e32 v5, v6, v10
	v_pk_add_f32 v[2:3], v[2:3], v[10:11] neg_lo:[0,1] neg_hi:[0,1]
	v_sub_f32_e32 v5, v12, v5
	v_add_f32_e32 v2, v2, v5
	v_add_f32_e32 v2, v2, v3
	v_add_f32_e32 v2, v4, v2
	v_cndmask_b32_e32 v2, v72, v2, vcc
	v_cmp_ngt_f32_e32 vcc, -1.0, v16
	s_nop 1
	v_cndmask_b32_e32 v2, v73, v2, vcc
	v_cmp_neq_f32_e32 vcc, -1.0, v16
	s_nop 1
	v_cndmask_b32_e32 v2, v74, v2, vcc
	v_cmp_lt_f32_e64 vcc, |v16|, s15
	s_nop 1
	v_cndmask_b32_e32 v2, v2, v16, vcc
.LBB0_309:
	s_or_b64 exec, exec, s[12:13]
	v_readlane_b32 s36, v242, 2
	v_readlane_b32 s46, v242, 12
	v_readlane_b32 s47, v242, 13
	v_lshl_add_u32 v4, v75, 2, 0
	v_add_u32_e32 v4, 0x3000, v4
	v_readlane_b32 s37, v242, 3
	v_readlane_b32 s38, v242, 4
	v_readlane_b32 s39, v242, 5
	v_mov_b32_e32 v3, v254
	v_readlane_b32 s40, v242, 6
	v_readlane_b32 s41, v242, 7
	v_readlane_b32 s42, v242, 8
	v_readlane_b32 s43, v242, 9
	v_readlane_b32 s44, v242, 10
	v_readlane_b32 s45, v242, 11
	v_readlane_b32 s48, v242, 14
	v_readlane_b32 s49, v242, 15
	v_readlane_b32 s50, v242, 16
	v_readlane_b32 s51, v242, 17
	s_waitcnt vmcnt(0)
	v_mul_f32_e32 v3, 0x3fb8aa3b, v3
	v_exp_f32_e32 v3, v3
	s_nop 0
	v_mul_f32_e64 v3, v3, -v2
	v_mul_f32_e32 v3, 0x3fb8aa3b, v3
	v_exp_f32_e32 v3, v3
	ds_write2_b32 v4, v2, v3 offset1:32
	v_mov_b64_e32 v[2:3], v[18:19]
